# nt stores also in the prologue conversion phase (LN phases already nt), on aligned GEMM K-loops + MMA-path cleanup
# speedup vs baseline: 1.0069x; 1.0013x over previous
.LBB0_95:
	s_waitcnt lgkmcnt(0)
	v_or_b32_e32 v2, s17, v41
	v_mad_i64_i32 v[90:91], s[40:41], v2, s60, 0
	v_lshl_add_u64 v[90:91], v[90:91], 1, s[36:37]
	v_lshl_add_u64 v[90:91], s[6:7], 1, v[90:91]
	v_lshlrev_b32_e32 v2, 1, v44
	v_lshl_add_u64 v[90:91], v[90:91], 0, v[2:3]
	global_store_dwordx4 v[90:91], v[36:39], off nt

.LBB0_101:
	s_waitcnt lgkmcnt(0)
	v_or_b32_e32 v2, s17, v46
	v_mad_i64_i32 v[90:91], s[40:41], v2, s60, 0
	v_lshl_add_u64 v[90:91], v[90:91], 1, s[36:37]
	v_lshl_add_u64 v[90:91], s[6:7], 1, v[90:91]
	v_lshlrev_b32_e32 v2, 1, v44
	v_lshl_add_u64 v[90:91], v[90:91], 0, v[2:3]
	global_store_dwordx4 v[90:91], v[36:39], off nt

.LBB0_107:
	s_waitcnt lgkmcnt(0)
	v_or_b32_e32 v2, s17, v47
	v_mad_i64_i32 v[90:91], s[40:41], v2, s60, 0
	v_lshl_add_u64 v[90:91], v[90:91], 1, s[36:37]
	v_lshl_add_u64 v[90:91], s[6:7], 1, v[90:91]
	v_lshlrev_b32_e32 v2, 1, v44
	v_lshl_add_u64 v[90:91], v[90:91], 0, v[2:3]
	global_store_dwordx4 v[90:91], v[36:39], off nt

.LBB0_113:
	s_waitcnt lgkmcnt(0)
	v_or_b32_e32 v2, s17, v48
	v_mad_i64_i32 v[90:91], s[40:41], v2, s60, 0
	v_lshl_add_u64 v[90:91], v[90:91], 1, s[36:37]
	v_lshl_add_u64 v[90:91], s[6:7], 1, v[90:91]
	v_lshlrev_b32_e32 v2, 1, v44
	v_lshl_add_u64 v[90:91], v[90:91], 0, v[2:3]
	global_store_dwordx4 v[90:91], v[36:39], off nt

.LBB0_121:
	v_or_b32_e32 v82, s17, v41
	v_mad_i64_i32 v[82:83], s[6:7], v82, s59, 0
	v_lshl_add_u64 v[82:83], v[82:83], 1, s[30:31]
	v_lshl_add_u64 v[82:83], s[4:5], 1, v[82:83]
	v_lshl_add_u64 v[82:83], v[82:83], 0, v[2:3]
	global_store_dwordx4 v[82:83], v[36:39], off nt

.LBB0_127:
	s_waitcnt lgkmcnt(0)
	v_or_b32_e32 v82, s17, v46
	v_mad_i64_i32 v[82:83], s[6:7], v82, s59, 0
	v_lshl_add_u64 v[82:83], v[82:83], 1, s[30:31]
	v_lshl_add_u64 v[82:83], s[4:5], 1, v[82:83]
	v_lshl_add_u64 v[82:83], v[82:83], 0, v[2:3]
	global_store_dwordx4 v[82:83], v[36:39], off nt

.LBB0_133:
	s_waitcnt lgkmcnt(0)
	v_or_b32_e32 v82, s17, v47
	v_mad_i64_i32 v[82:83], s[6:7], v82, s59, 0
	v_lshl_add_u64 v[82:83], v[82:83], 1, s[30:31]
	v_lshl_add_u64 v[82:83], s[4:5], 1, v[82:83]
	v_lshl_add_u64 v[82:83], v[82:83], 0, v[2:3]
	global_store_dwordx4 v[82:83], v[36:39], off nt

.LBB0_139:
	s_cmp_eq_u32 s58, 2
	s_mov_b64 s[42:43], -1
	s_cbranch_scc0 .LBB0_141
	ds_read2_b32 v[36:37], v43 offset0:33 offset1:66
	ds_read2_b32 v[38:39], v43 offset0:99 offset1:132
	ds_read2_b32 v[90:91], v43 offset0:165 offset1:198
	s_waitcnt lgkmcnt(3)
	v_mul_f32_e32 v89, 0x42800000, v2
	s_waitcnt lgkmcnt(2)
	v_mul_f32_e32 v92, 0x42800000, v36
	v_mov_b32_e32 v36, v3
	v_cvt_pk_fp8_f32 v36, v89, v92
	s_waitcnt lgkmcnt(0)
	v_mul_f32_e32 v89, 0x42800000, v90
	ds_read_b32 v90, v43 offset:924
	v_mul_f32_e32 v93, 0x42800000, v37
	v_mul_f32_e32 v39, 0x42800000, v39
	v_mov_b32_e32 v37, v3
	v_cvt_pk_fp8_f32 v37, v39, v89
	v_mul_f32_e32 v38, 0x42800000, v38
	v_cvt_pk_fp8_f32 v36, v93, v38 op_sel:[0,0,1]
	v_mul_f32_e32 v38, 0x42800000, v91
	s_waitcnt lgkmcnt(0)
	v_mul_f32_e32 v39, 0x42800000, v90
	v_cvt_pk_fp8_f32 v37, v38, v39 op_sel:[0,0,1]
	v_or_b32_e32 v89, s17, v41
	v_mov_b64_e32 v[38:39], s[36:37]
	v_mad_i64_i32 v[38:39], s[42:43], v89, s60, v[38:39]
	v_lshl_add_u64 v[38:39], v[38:39], 0, s[6:7]
	v_lshl_add_u64 v[38:39], v[38:39], 0, v[44:45]
	global_store_dwordx2 v[38:39], v[36:37], off nt
	s_mov_b64 s[42:43], 0

.LBB0_145:
	s_cmp_eq_u32 s58, 2
	s_mov_b64 s[42:43], -1
	s_cbranch_scc0 .LBB0_147
	ds_read2_b32 v[36:37], v43 offset0:41 offset1:74
	ds_read2_b32 v[38:39], v43 offset0:107 offset1:140
	ds_read2_b32 v[90:91], v43 offset0:173 offset1:206
	s_waitcnt lgkmcnt(3)
	v_mul_f32_e32 v89, 0x42800000, v2
	s_waitcnt lgkmcnt(2)
	v_mul_f32_e32 v92, 0x42800000, v36
	v_mov_b32_e32 v36, v3
	v_cvt_pk_fp8_f32 v36, v89, v92
	s_waitcnt lgkmcnt(0)
	v_mul_f32_e32 v89, 0x42800000, v90
	ds_read_b32 v90, v43 offset:956
	v_mul_f32_e32 v93, 0x42800000, v37
	v_mul_f32_e32 v39, 0x42800000, v39
	v_mov_b32_e32 v37, v3
	v_cvt_pk_fp8_f32 v37, v39, v89
	v_mul_f32_e32 v38, 0x42800000, v38
	v_cvt_pk_fp8_f32 v36, v93, v38 op_sel:[0,0,1]
	v_mul_f32_e32 v38, 0x42800000, v91
	s_waitcnt lgkmcnt(0)
	v_mul_f32_e32 v39, 0x42800000, v90
	v_cvt_pk_fp8_f32 v37, v38, v39 op_sel:[0,0,1]
	v_or_b32_e32 v89, s17, v46
	v_mov_b64_e32 v[38:39], s[36:37]
	v_mad_i64_i32 v[38:39], s[42:43], v89, s60, v[38:39]
	v_lshl_add_u64 v[38:39], v[38:39], 0, s[6:7]
	v_lshl_add_u64 v[38:39], v[38:39], 0, v[44:45]
	global_store_dwordx2 v[38:39], v[36:37], off nt
	s_mov_b64 s[42:43], 0

.LBB0_151:
	s_cmp_eq_u32 s58, 2
	s_mov_b64 s[42:43], -1
	s_cbranch_scc0 .LBB0_153
	ds_read2_b32 v[36:37], v43 offset0:49 offset1:82
	ds_read2_b32 v[38:39], v43 offset0:115 offset1:148
	ds_read2_b32 v[90:91], v43 offset0:181 offset1:214
	s_waitcnt lgkmcnt(3)
	v_mul_f32_e32 v89, 0x42800000, v2
	s_waitcnt lgkmcnt(2)
	v_mul_f32_e32 v92, 0x42800000, v36
	v_mov_b32_e32 v36, v3
	v_cvt_pk_fp8_f32 v36, v89, v92
	s_waitcnt lgkmcnt(0)
	v_mul_f32_e32 v89, 0x42800000, v90
	ds_read_b32 v90, v43 offset:988
	v_mul_f32_e32 v93, 0x42800000, v37
	v_mul_f32_e32 v39, 0x42800000, v39
	v_mov_b32_e32 v37, v3
	v_cvt_pk_fp8_f32 v37, v39, v89
	v_mul_f32_e32 v38, 0x42800000, v38
	v_cvt_pk_fp8_f32 v36, v93, v38 op_sel:[0,0,1]
	v_mul_f32_e32 v38, 0x42800000, v91
	s_waitcnt lgkmcnt(0)
	v_mul_f32_e32 v39, 0x42800000, v90
	v_cvt_pk_fp8_f32 v37, v38, v39 op_sel:[0,0,1]
	v_or_b32_e32 v89, s17, v47
	v_mov_b64_e32 v[38:39], s[36:37]
	v_mad_i64_i32 v[38:39], s[42:43], v89, s60, v[38:39]
	v_lshl_add_u64 v[38:39], v[38:39], 0, s[6:7]
	v_lshl_add_u64 v[38:39], v[38:39], 0, v[44:45]
	global_store_dwordx2 v[38:39], v[36:37], off nt
	s_mov_b64 s[42:43], 0

.LBB0_157:
	s_cmp_eq_u32 s58, 2
	s_mov_b64 s[42:43], -1
	s_cbranch_scc0 .LBB0_159
	ds_read2_b32 v[36:37], v43 offset0:57 offset1:90
	ds_read2_b32 v[38:39], v43 offset0:123 offset1:156
	ds_read2_b32 v[90:91], v43 offset0:189 offset1:222
	s_waitcnt lgkmcnt(3)
	v_mul_f32_e32 v89, 0x42800000, v2
	s_waitcnt lgkmcnt(2)
	v_mul_f32_e32 v92, 0x42800000, v36
	v_mov_b32_e32 v36, v3
	v_cvt_pk_fp8_f32 v36, v89, v92
	s_waitcnt lgkmcnt(0)
	v_mul_f32_e32 v89, 0x42800000, v90
	ds_read_b32 v90, v43 offset:1020
	v_mul_f32_e32 v93, 0x42800000, v37
	v_mul_f32_e32 v39, 0x42800000, v39
	v_mov_b32_e32 v37, v3
	v_cvt_pk_fp8_f32 v37, v39, v89
	v_mul_f32_e32 v38, 0x42800000, v38
	v_cvt_pk_fp8_f32 v36, v93, v38 op_sel:[0,0,1]
	v_mul_f32_e32 v38, 0x42800000, v91
	s_waitcnt lgkmcnt(0)
	v_mul_f32_e32 v39, 0x42800000, v90
	v_cvt_pk_fp8_f32 v37, v38, v39 op_sel:[0,0,1]
	v_or_b32_e32 v89, s17, v48
	v_mov_b64_e32 v[38:39], s[36:37]
	v_mad_i64_i32 v[38:39], s[42:43], v89, s60, v[38:39]
	v_lshl_add_u64 v[38:39], v[38:39], 0, s[6:7]
	v_lshl_add_u64 v[38:39], v[38:39], 0, v[44:45]
	global_store_dwordx2 v[38:39], v[36:37], off nt
	s_mov_b64 s[42:43], 0

.LBB0_163:
	s_cmp_eq_u32 s53, 2
	s_mov_b64 s[40:41], -1
	s_cbranch_scc0 .LBB0_165
	ds_read2_b32 v[36:37], v43 offset0:33 offset1:66
	ds_read2_b32 v[38:39], v43 offset0:99 offset1:132
	ds_read2_b32 v[82:83], v43 offset0:165 offset1:198
	s_waitcnt lgkmcnt(3)
	v_mul_f32_e32 v84, 0x42800000, v2
	s_waitcnt lgkmcnt(2)
	v_mul_f32_e32 v85, 0x42800000, v36
	v_mov_b32_e32 v36, v3
	v_cvt_pk_fp8_f32 v36, v84, v85
	ds_read_b32 v84, v43 offset:924
	v_mul_f32_e32 v86, 0x42800000, v37
	s_waitcnt lgkmcnt(2)
	v_mul_f32_e32 v39, 0x42800000, v39
	s_waitcnt lgkmcnt(1)
	v_mul_f32_e32 v82, 0x42800000, v82
	v_mov_b32_e32 v37, v3
	v_cvt_pk_fp8_f32 v37, v39, v82
	v_mul_f32_e32 v38, 0x42800000, v38
	v_cvt_pk_fp8_f32 v36, v86, v38 op_sel:[0,0,1]
	v_mul_f32_e32 v38, 0x42800000, v83
	s_waitcnt lgkmcnt(0)
	v_mul_f32_e32 v39, 0x42800000, v84
	v_cvt_pk_fp8_f32 v37, v38, v39 op_sel:[0,0,1]
	v_or_b32_e32 v82, s17, v41
	v_mov_b64_e32 v[38:39], s[30:31]
	v_mad_i64_i32 v[38:39], s[40:41], v82, s59, v[38:39]
	v_lshl_add_u64 v[38:39], v[38:39], 0, s[4:5]
	v_lshl_add_u64 v[38:39], v[38:39], 0, v[44:45]
	global_store_dwordx2 v[38:39], v[36:37], off nt
	s_mov_b64 s[40:41], 0

.LBB0_169:
	s_cmp_eq_u32 s53, 2
	s_mov_b64 s[40:41], -1
	s_cbranch_scc0 .LBB0_171
	ds_read2_b32 v[36:37], v43 offset0:41 offset1:74
	ds_read2_b32 v[38:39], v43 offset0:107 offset1:140
	ds_read2_b32 v[84:85], v43 offset0:173 offset1:206
	s_waitcnt lgkmcnt(3)
	v_mul_f32_e32 v83, 0x42800000, v82
	s_waitcnt lgkmcnt(2)
	v_mul_f32_e32 v86, 0x42800000, v36
	v_mov_b32_e32 v36, v3
	v_cvt_pk_fp8_f32 v36, v83, v86
	s_waitcnt lgkmcnt(0)
	v_mul_f32_e32 v83, 0x42800000, v84
	ds_read_b32 v84, v43 offset:956
	v_mul_f32_e32 v87, 0x42800000, v37
	v_mul_f32_e32 v39, 0x42800000, v39
	v_mov_b32_e32 v37, v3
	v_cvt_pk_fp8_f32 v37, v39, v83
	v_mul_f32_e32 v38, 0x42800000, v38
	v_cvt_pk_fp8_f32 v36, v87, v38 op_sel:[0,0,1]
	v_mul_f32_e32 v38, 0x42800000, v85
	s_waitcnt lgkmcnt(0)
	v_mul_f32_e32 v39, 0x42800000, v84
	v_cvt_pk_fp8_f32 v37, v38, v39 op_sel:[0,0,1]
	v_or_b32_e32 v83, s17, v46
	v_mov_b64_e32 v[38:39], s[30:31]
	v_mad_i64_i32 v[38:39], s[40:41], v83, s59, v[38:39]
	v_lshl_add_u64 v[38:39], v[38:39], 0, s[4:5]
	v_lshl_add_u64 v[38:39], v[38:39], 0, v[44:45]
	global_store_dwordx2 v[38:39], v[36:37], off nt
	s_mov_b64 s[40:41], 0

.LBB0_175:
	s_cmp_eq_u32 s53, 2
	s_mov_b64 s[40:41], -1
	s_cbranch_scc0 .LBB0_177
	ds_read2_b32 v[36:37], v43 offset0:49 offset1:82
	ds_read2_b32 v[38:39], v43 offset0:115 offset1:148
	ds_read2_b32 v[84:85], v43 offset0:181 offset1:214
	s_waitcnt lgkmcnt(3)
	v_mul_f32_e32 v83, 0x42800000, v82
	s_waitcnt lgkmcnt(2)
	v_mul_f32_e32 v86, 0x42800000, v36
	v_mov_b32_e32 v36, v3
	v_cvt_pk_fp8_f32 v36, v83, v86
	s_waitcnt lgkmcnt(0)
	v_mul_f32_e32 v83, 0x42800000, v84
	ds_read_b32 v84, v43 offset:988
	v_mul_f32_e32 v87, 0x42800000, v37
	v_mul_f32_e32 v39, 0x42800000, v39
	v_mov_b32_e32 v37, v3
	v_cvt_pk_fp8_f32 v37, v39, v83
	v_mul_f32_e32 v38, 0x42800000, v38
	v_cvt_pk_fp8_f32 v36, v87, v38 op_sel:[0,0,1]
	v_mul_f32_e32 v38, 0x42800000, v85
	s_waitcnt lgkmcnt(0)
	v_mul_f32_e32 v39, 0x42800000, v84
	v_cvt_pk_fp8_f32 v37, v38, v39 op_sel:[0,0,1]
	v_or_b32_e32 v83, s17, v47
	v_mov_b64_e32 v[38:39], s[30:31]
	v_mad_i64_i32 v[38:39], s[40:41], v83, s59, v[38:39]
	v_lshl_add_u64 v[38:39], v[38:39], 0, s[4:5]
	v_lshl_add_u64 v[38:39], v[38:39], 0, v[44:45]
	global_store_dwordx2 v[38:39], v[36:37], off nt
	s_mov_b64 s[40:41], 0

.LBB0_181:
	s_cmp_eq_u32 s53, 2
	s_mov_b64 s[40:41], -1
	s_cbranch_scc0 .LBB0_183
	ds_read2_b32 v[36:37], v43 offset0:57 offset1:90
	ds_read2_b32 v[38:39], v43 offset0:123 offset1:156
	ds_read2_b32 v[84:85], v43 offset0:189 offset1:222
	s_waitcnt lgkmcnt(3)
	v_mul_f32_e32 v83, 0x42800000, v82
	s_waitcnt lgkmcnt(2)
	v_mul_f32_e32 v86, 0x42800000, v36
	v_mov_b32_e32 v36, v3
	v_cvt_pk_fp8_f32 v36, v83, v86
	s_waitcnt lgkmcnt(0)
	v_mul_f32_e32 v83, 0x42800000, v84
	ds_read_b32 v84, v43 offset:1020
	v_mul_f32_e32 v87, 0x42800000, v37
	v_mul_f32_e32 v39, 0x42800000, v39
	v_mov_b32_e32 v37, v3
	v_cvt_pk_fp8_f32 v37, v39, v83
	v_mul_f32_e32 v38, 0x42800000, v38
	v_cvt_pk_fp8_f32 v36, v87, v38 op_sel:[0,0,1]
	v_mul_f32_e32 v38, 0x42800000, v85
	s_waitcnt lgkmcnt(0)
	v_mul_f32_e32 v39, 0x42800000, v84
	v_cvt_pk_fp8_f32 v37, v38, v39 op_sel:[0,0,1]
	v_or_b32_e32 v83, s17, v48
	v_mov_b64_e32 v[38:39], s[30:31]
	v_mad_i64_i32 v[38:39], s[40:41], v83, s59, v[38:39]
	v_lshl_add_u64 v[38:39], v[38:39], 0, s[4:5]
	v_lshl_add_u64 v[38:39], v[38:39], 0, v[44:45]
	global_store_dwordx2 v[38:39], v[36:37], off nt
	s_mov_b64 s[40:41], 0

.LBB0_187:
	s_waitcnt lgkmcnt(0)
	v_or_b32_e32 v82, s17, v48
	v_mad_i64_i32 v[82:83], s[6:7], v82, s59, 0
	v_lshl_add_u64 v[82:83], v[82:83], 1, s[30:31]
	v_lshl_add_u64 v[82:83], s[4:5], 1, v[82:83]
	v_lshl_add_u64 v[82:83], v[82:83], 0, v[2:3]
	global_store_dwordx4 v[82:83], v[36:39], off nt
	s_branch .LBB0_18

.LBB0_190:
	v_lshl_add_u64 v[38:39], v[22:23], 0, s[34:35]
	global_load_dwordx4 v[26:29], v[22:23], off nt
	global_load_dwordx4 v[30:33], v[22:23], off offset:16 nt
	v_lshl_add_u64 v[46:47], v[38:39], 0, 16
	global_load_dwordx4 v[34:37], v[38:39], off offset:32 nt
	global_load_dwordx4 v[42:45], v[38:39], off offset:16 nt
	v_lshl_add_u64 v[38:39], v[46:47], 0, s[34:35]
	global_load_dwordx4 v[46:49], v[38:39], off offset:16 nt
	global_load_dwordx4 v[50:53], v[38:39], off offset:32 nt
	v_lshl_add_u64 v[38:39], v[38:39], 0, 16
	v_lshl_add_u64 v[38:39], v[38:39], 0, s[34:35]
	global_load_dwordx4 v[54:57], v[38:39], off offset:16 nt
	global_load_dwordx4 v[58:61], v[38:39], off offset:32 nt
	v_mov_b32_e32 v66, 0
	v_mov_b32_e32 v67, 0
	s_waitcnt vmcnt(17)
	v_mov_b32_e32 v72, 0
	s_waitcnt vmcnt(16)
	v_mov_b32_e32 v73, 0
	s_waitcnt vmcnt(11)
	v_mov_b32_e32 v78, 0
	s_waitcnt vmcnt(10)
	v_mov_b32_e32 v79, 0
	s_add_u32 s19, s4, s4
	v_mov_b32_e32 v84, 0
	v_mov_b32_e32 v85, 0
	s_addc_u32 s25, s5, s5
	s_add_u32 s24, s19, s19
	s_addc_u32 s25, s25, s25
	v_lshl_add_u64 v[38:39], s[42:43], 0, v[6:7]
	v_lshl_add_u64 v[70:71], s[42:43], 0, v[18:19]
	v_lshl_add_u64 v[76:77], s[42:43], 0, v[10:11]
	v_lshl_add_u64 v[82:83], s[42:43], 0, v[14:15]
	s_add_u32 s42, s42, s14
	v_lshl_add_u64 v[68:69], s[40:41], 0, v[8:9]
	s_addc_u32 s43, s43, s15
	v_lshl_add_u64 v[74:75], s[40:41], 0, v[20:21]
	s_waitcnt vmcnt(8)
	v_lshl_add_u64 v[80:81], s[40:41], 0, v[12:13]
	v_lshl_add_u64 v[86:87], s[40:41], 0, v[16:17]
	v_lshl_add_u64 v[24:25], s[24:25], 0, v[24:25]
	s_add_u32 s40, s40, s16
	v_cmp_lt_u64_e32 vcc, s[38:39], v[24:25]
	s_addc_u32 s41, s41, s17
	v_lshl_add_u64 v[22:23], v[22:23], 0, s[30:31]
	s_or_b64 s[36:37], vcc, s[36:37]
	s_waitcnt vmcnt(7)
	v_cvt_pk_bf16_f32 v62, v26, v27
	v_cvt_pk_fp8_f32 v66, v26, v27
	s_waitcnt vmcnt(6)
	v_cvt_pk_fp8_f32 v67, v30, v31
	s_waitcnt vmcnt(4)
	v_cvt_pk_fp8_f32 v72, v42, v43
	v_cvt_pk_fp8_f32 v73, v34, v35
	s_waitcnt vmcnt(3)
	v_cvt_pk_fp8_f32 v78, v46, v47
	s_waitcnt vmcnt(2)
	v_cvt_pk_fp8_f32 v79, v50, v51
	v_cvt_pk_fp8_f32 v66, v28, v29 op_sel:[0,0,1]
	v_cvt_pk_fp8_f32 v67, v32, v33 op_sel:[0,0,1]
	s_waitcnt vmcnt(1)
	v_cvt_pk_fp8_f32 v84, v54, v55
	s_waitcnt vmcnt(0)
	v_cvt_pk_fp8_f32 v85, v58, v59
	v_cvt_pk_fp8_f32 v72, v44, v45 op_sel:[0,0,1]
	v_cvt_pk_fp8_f32 v73, v36, v37 op_sel:[0,0,1]
	v_cvt_pk_fp8_f32 v78, v48, v49 op_sel:[0,0,1]
	v_cvt_pk_fp8_f32 v79, v52, v53 op_sel:[0,0,1]
	v_cvt_pk_bf16_f32 v63, v28, v29
	v_cvt_pk_bf16_f32 v64, v30, v31
	v_cvt_pk_bf16_f32 v65, v32, v33
	global_store_dwordx4 v[38:39], v[62:65], off nt
	global_store_dwordx2 v[68:69], v[66:67], off nt
	v_cvt_pk_bf16_f32 v26, v42, v43
	v_cvt_pk_bf16_f32 v27, v44, v45
	v_cvt_pk_bf16_f32 v28, v34, v35
	v_cvt_pk_bf16_f32 v29, v36, v37
	v_cvt_pk_fp8_f32 v84, v56, v57 op_sel:[0,0,1]
	v_cvt_pk_fp8_f32 v85, v60, v61 op_sel:[0,0,1]
	global_store_dwordx4 v[70:71], v[26:29], off nt
	global_store_dwordx2 v[74:75], v[72:73], off nt
	s_nop 0
	v_cvt_pk_bf16_f32 v26, v46, v47
	v_cvt_pk_bf16_f32 v27, v48, v49
	v_cvt_pk_bf16_f32 v28, v50, v51
	v_cvt_pk_bf16_f32 v29, v52, v53
	global_store_dwordx4 v[76:77], v[26:29], off nt
	global_store_dwordx2 v[80:81], v[78:79], off nt
	s_nop 0
	v_cvt_pk_bf16_f32 v26, v54, v55
	v_cvt_pk_bf16_f32 v27, v56, v57
	v_cvt_pk_bf16_f32 v28, v58, v59
	v_cvt_pk_bf16_f32 v29, v60, v61
	global_store_dwordx4 v[82:83], v[26:29], off nt
	global_store_dwordx2 v[86:87], v[84:85], off nt
	s_andn2_b64 exec, exec, s[36:37]
	s_cbranch_execnz .LBB0_190

.LBB0_193:
	s_waitcnt vmcnt(4)
	v_lshl_add_u64 v[30:31], v[4:5], 0, s[8:9]
	global_load_dwordx4 v[14:17], v[4:5], off nt
	global_load_dwordx4 v[18:21], v[4:5], off offset:16 nt
	global_load_dwordx4 v[22:25], v[30:31], off offset:16 nt
	global_load_dwordx4 v[26:29], v[30:31], off offset:32 nt
	v_lshl_add_u64 v[30:31], v[30:31], 0, 16
	v_lshl_add_u64 v[38:39], v[30:31], 0, s[8:9]
	global_load_dwordx4 v[30:33], v[38:39], off offset:16 nt
	global_load_dwordx4 v[34:37], v[38:39], off offset:32 nt
	v_lshl_add_u64 v[38:39], v[38:39], 0, 16
	v_lshl_add_u64 v[46:47], v[38:39], 0, s[8:9]
	global_load_dwordx4 v[38:41], v[46:47], off offset:16 nt
	global_load_dwordx4 v[42:45], v[46:47], off offset:32 nt
	s_add_u32 s3, s4, s4
	s_addc_u32 s19, s5, s5
	s_add_u32 s18, s3, s3
	s_addc_u32 s19, s19, s19
	v_lshl_add_u64 v[46:47], s[14:15], 0, v[6:7]
	v_lshl_add_u64 v[48:49], s[14:15], 0, v[12:13]
	v_lshl_add_u64 v[50:51], s[14:15], 0, v[8:9]
	v_lshl_add_u64 v[52:53], s[14:15], 0, v[10:11]
	v_lshl_add_u64 v[2:3], s[18:19], 0, v[2:3]
	s_add_u32 s14, s14, s16
	s_addc_u32 s15, s15, s17
	v_cmp_lt_u64_e32 vcc, s[30:31], v[2:3]
	v_lshl_add_u64 v[4:5], v[4:5], 0, s[6:7]
	s_or_b64 s[10:11], vcc, s[10:11]
	s_waitcnt vmcnt(7)
	v_cvt_pk_bf16_f32 v14, v14, v15
	v_cvt_pk_bf16_f32 v15, v16, v17
	s_waitcnt vmcnt(6)
	v_cvt_pk_bf16_f32 v16, v18, v19
	v_cvt_pk_bf16_f32 v17, v20, v21
	global_store_dwordx4 v[46:47], v[14:17], off nt
	s_waitcnt vmcnt(6)
	s_nop 0
	v_cvt_pk_bf16_f32 v14, v22, v23
	v_cvt_pk_bf16_f32 v15, v24, v25
	s_waitcnt vmcnt(5)
	v_cvt_pk_bf16_f32 v16, v26, v27
	v_cvt_pk_bf16_f32 v17, v28, v29
	global_store_dwordx4 v[48:49], v[14:17], off nt
	s_waitcnt vmcnt(5)
	s_nop 0
	v_cvt_pk_bf16_f32 v14, v30, v31
	v_cvt_pk_bf16_f32 v15, v32, v33
	s_waitcnt vmcnt(4)
	v_cvt_pk_bf16_f32 v16, v34, v35
	v_cvt_pk_bf16_f32 v17, v36, v37
	global_store_dwordx4 v[50:51], v[14:17], off nt
	s_waitcnt vmcnt(4)
	s_nop 0
	v_cvt_pk_bf16_f32 v14, v38, v39
	v_cvt_pk_bf16_f32 v15, v40, v41
	s_waitcnt vmcnt(3)
	v_cvt_pk_bf16_f32 v16, v42, v43
	v_cvt_pk_bf16_f32 v17, v44, v45
	global_store_dwordx4 v[52:53], v[14:17], off nt
	s_andn2_b64 exec, exec, s[10:11]
	s_cbranch_execnz .LBB0_193
